# best + NA even-row half: 15 address '+0' adds removed (ds_read takes the source register)
# speedup vs baseline: 1.0109x; 1.0062x over previous
.LBB0_307:
	s_add_i32 s16, s47, s49
	s_add_i32 s51, s16, -2
	s_cmp_ge_u32 s51, s24
	s_cselect_b64 s[16:17], -1, 0
	s_cmp_lt_u32 s51, s31
	s_cselect_b64 s[52:53], -1, 0
	s_and_b64 s[16:17], s[16:17], s[52:53]
	s_andn2_b64 vcc, exec, s[16:17]
	s_cbranch_vccnz .LBB0_309
	v_add_u32_e32 v85, v118, v107
	ds_read_b128 v[194:197], v85
	ds_read_b128 v[202:205], v85 offset:2048
	v_add_u32_e32 v193, v118, v108
	ds_read_b128 v[198:201], v193
	ds_read_b128 v[206:209], v193 offset:2048
	s_waitcnt lgkmcnt(3)
	v_mfma_f32_16x16x32_bf16 v[194:197], v[194:197], v[20:23], 0
	s_waitcnt lgkmcnt(1)
	v_mfma_f32_16x16x32_bf16 v[194:197], v[198:201], v[24:27], v[194:197]
	ds_read_b32 v198, v192
	ds_read_b32 v199, v191
	ds_read_b32 v200, v190
	ds_read_b32 v210, v189
	ds_read_b32 v211, v188
	ds_read_b32 v85, v187
	ds_read_b32 v212, v186
	ds_read_b32 v193, v185
	s_waitcnt lgkmcnt(7)
	v_add_f32_e32 v194, v194, v198
	v_exp_f32_e32 v214, v194
	s_waitcnt lgkmcnt(6)
	v_add_f32_e32 v194, v195, v199
	v_exp_f32_e32 v222, v194
	s_waitcnt lgkmcnt(5)
	v_add_f32_e32 v194, v196, v200
	v_mfma_f32_16x16x32_bf16 v[198:201], v[202:205], v[20:23], 0
	v_exp_f32_e32 v224, v194
	s_waitcnt lgkmcnt(4)
	v_add_f32_e32 v194, v197, v210
	v_exp_f32_e32 v226, v194
	v_mfma_f32_16x16x32_bf16 v[194:197], v[206:209], v[24:27], v[198:201]
	v_add_u32_e32 v215, 0, v178
	s_nop 1
	v_cvt_pk_bf16_f32 v198, v214, v222
	v_cvt_pk_bf16_f32 v199, v224, v226
	s_waitcnt lgkmcnt(2)
	s_nop 1
	v_add_f32_e32 v85, v195, v85
	v_exp_f32_e32 v230, v85
	s_waitcnt lgkmcnt(1)
	v_add_f32_e32 v85, v196, v212
	v_add_f32_e32 v194, v194, v211
	v_exp_f32_e32 v232, v85
	s_waitcnt lgkmcnt(0)
	v_add_f32_e32 v85, v197, v193
	v_add_u32_e32 v193, v119, v111
	v_exp_f32_e32 v228, v194
	ds_read_b64_tr_b16 v[194:195], v193 offset:8192
	ds_read_b64_tr_b16 v[196:197], v193 offset:10240
	v_exp_f32_e32 v234, v85
	v_add_u32_e32 v85, v119, v112
	v_cvt_pk_bf16_f32 v200, v228, v230
	ds_read_b64_tr_b16 v[202:203], v85 offset:8192
	ds_read_b64_tr_b16 v[204:205], v85 offset:10240
	v_cvt_pk_bf16_f32 v201, v232, v234
	v_add_u32_e32 v85, v119, v113
	v_add_u32_e32 v193, v120, v108
	s_waitcnt lgkmcnt(2)
	v_mfma_f32_16x16x32_bf16 v[76:79], v[194:197], v[198:201], v[76:79]
	ds_read_b64_tr_b16 v[194:195], v85 offset:8192
	ds_read_b64_tr_b16 v[196:197], v85 offset:10240
	v_add_u32_e32 v85, v119, v114
	s_waitcnt lgkmcnt(2)
	v_mfma_f32_16x16x32_bf16 v[64:67], v[202:205], v[198:201], v[64:67]
	ds_read_b64_tr_b16 v[202:203], v85 offset:8192
	ds_read_b64_tr_b16 v[204:205], v85 offset:10240
	v_add_u32_e32 v85, v120, v107
	ds_read_b128 v[206:209], v85 offset:2048
	s_waitcnt lgkmcnt(3)
	v_mfma_f32_16x16x32_bf16 v[72:75], v[194:197], v[198:201], v[72:75]
	ds_read_b128 v[194:197], v85
	ds_read_b128 v[210:213], v193
	ds_read_b128 v[218:221], v193 offset:2048
	s_waitcnt lgkmcnt(2)
	v_mfma_f32_16x16x32_bf16 v[194:197], v[194:197], v[36:39], 0
	s_waitcnt lgkmcnt(1)
	v_mfma_f32_16x16x32_bf16 v[194:197], v[210:213], v[40:43], v[194:197]
	ds_read_b32 v85, v184
	ds_read_b32 v193, v183
	ds_read_b32 v210, v182
	ds_read_b32 v211, v181
	ds_read_b32 v212, v180
	ds_read_b32 v213, v179
	ds_read_b32 v233, v215
	ds_read_b32 v217, v177
	s_waitcnt lgkmcnt(7)
	v_add_f32_e32 v85, v194, v85
	v_exp_f32_e32 v215, v85
	s_waitcnt lgkmcnt(6)
	v_add_f32_e32 v85, v195, v193
	v_exp_f32_e32 v223, v85
	v_mfma_f32_16x16x32_bf16 v[68:71], v[202:205], v[198:201], v[68:71]
	v_add_f32_e64 v194, v214, 0
	v_add_f32_e64 v195, v215, 0
	s_waitcnt lgkmcnt(5)
	v_add_f32_e32 v85, v196, v210
	v_pk_add_f32 v[202:203], v[194:195], v[222:223]
	v_mfma_f32_16x16x32_bf16 v[198:201], v[206:209], v[36:39], 0
	v_exp_f32_e32 v225, v85
	s_waitcnt lgkmcnt(4)
	v_add_f32_e32 v85, v197, v211
	v_exp_f32_e32 v227, v85
	v_mfma_f32_16x16x32_bf16 v[194:197], v[218:221], v[40:43], v[198:201]
	v_add_f32_e64 v210, v202, v224
	v_add_f32_e64 v211, v203, v225
	s_waitcnt lgkmcnt(3)
	s_nop 4
	v_add_f32_e32 v85, v194, v212
	v_exp_f32_e32 v229, v85
	s_waitcnt lgkmcnt(2)
	v_add_f32_e32 v85, v195, v213
	v_exp_f32_e32 v231, v85
	s_waitcnt lgkmcnt(1)
	v_add_f32_e32 v85, v196, v233
	v_exp_f32_e32 v233, v85
	s_waitcnt lgkmcnt(0)
	v_add_f32_e32 v85, v197, v217
	v_exp_f32_e32 v235, v85
	v_add_u32_e32 v85, v121, v111
	ds_read_b64_tr_b16 v[198:199], v85 offset:8192
	ds_read_b64_tr_b16 v[200:201], v85 offset:10240
	v_add_u32_e32 v85, v121, v112
	ds_read_b64_tr_b16 v[202:203], v85 offset:8192
	ds_read_b64_tr_b16 v[204:205], v85 offset:10240
	v_add_u32_e32 v85, v121, v113
	v_cvt_pk_bf16_f32 v194, v215, v223
	v_cvt_pk_bf16_f32 v195, v225, v227
	v_cvt_pk_bf16_f32 v196, v229, v231
	v_cvt_pk_bf16_f32 v197, v233, v235
	ds_read_b64_tr_b16 v[206:207], v85 offset:8192
	ds_read_b64_tr_b16 v[208:209], v85 offset:10240
	v_add_u32_e32 v85, v121, v114
	s_waitcnt lgkmcnt(4)
	v_mfma_f32_16x16x32_bf16 v[60:63], v[198:201], v[194:197], v[60:63]
	ds_read_b64_tr_b16 v[198:199], v85 offset:8192
	ds_read_b64_tr_b16 v[200:201], v85 offset:10240
	s_waitcnt lgkmcnt(4)
	v_mfma_f32_16x16x32_bf16 v[56:59], v[202:205], v[194:197], v[56:59]
	v_add_f32_e64 v202, v210, v226
	v_add_f32_e64 v203, v211, v227
	v_pk_add_f32 v[202:203], v[202:203], v[228:229]
	s_waitcnt lgkmcnt(2)
	v_mfma_f32_16x16x32_bf16 v[52:55], v[206:209], v[194:197], v[52:55]
	v_add_f32_e64 v202, v202, v230
	v_add_f32_e64 v203, v203, v231
	v_pk_add_f32 v[202:203], v[202:203], v[232:233]
	s_waitcnt lgkmcnt(0)
	v_mfma_f32_16x16x32_bf16 v[44:47], v[198:201], v[194:197], v[44:47]
	v_add_f32_e64 v202, v202, v234
	v_add_f32_e64 v203, v203, v235
	v_pk_add_f32 v[102:103], v[202:203], v[102:103]
